# S5 pass 2: static s_setprio 1 for the delayed waves 4-7 (reset to 0 at the end of each job)
# speedup vs baseline: 1.0003x; 1.0003x over previous
.LBB0_275:
	s_mov_b64 s[18:19], 0
	s_setprio 0
	s_barrier

.LBB0_290:
	s_or_b64 exec, exec, s[18:19]
	v_mov_b32_e32 v75, v199
	v_lshl_add_u64 v[36:37], v[88:89], 0, v[74:75]
	global_load_dwordx4 v[40:43], v[90:91], off
	global_load_dwordx2 v[92:93], v[36:37], off
	s_lshl_b32 s52, s22, 1
	v_lshl_add_u64 v[76:77], v[60:61], 0, s[52:53]
	v_lshl_add_u64 v[86:87], v[70:71], 0, v[86:87]
	s_mov_b64 s[18:19], 0
	v_xor_b32_e32 v75, 0x80000000, v114
	v_xor_b32_e32 v114, 0x80000000, v115
	v_xor_b32_e32 v115, 0x80000000, v116
	v_xor_b32_e32 v116, 0x80000000, v117
	v_xor_b32_e32 v117, 0x80000000, v118
	v_xor_b32_e32 v118, 0x80000000, v119
	v_xor_b32_e32 v119, 0x80000000, v120
	v_xor_b32_e32 v120, 0x80000000, v121
	v_xor_b32_e32 v121, 0x80000000, v122
	v_xor_b32_e32 v122, 0x80000000, v123
	v_xor_b32_e32 v123, 0x80000000, v124
	v_xor_b32_e32 v124, 0x80000000, v125
	v_xor_b32_e32 v125, 0x80000000, v126
	v_xor_b32_e32 v126, 0x80000000, v127
	v_xor_b32_e32 v127, 0x80000000, v128
	v_xor_b32_e32 v128, 0x80000000, v129
	v_mov_b64_e32 v[88:89], v[46:47]
	s_waitcnt vmcnt(1)
	v_mov_b64_e32 v[36:37], v[40:41]
	s_waitcnt vmcnt(0)
	v_mov_b64_e32 v[90:91], v[92:93]
	v_mov_b64_e32 v[38:39], v[42:43]
	v_readfirstlane_b32 s0, v238
	s_nop 1
	s_cmpk_lt_u32 s0, 0x100
	s_cbranch_scc1 .Ls5_pass2_go
	s_sleep 20
	s_setprio 1
